# stack: Wb next-gate late loads hoisted, Uq epilogue sumsq loads issued together, weight-conversion gain loads issued up front
# speedup vs baseline: 1.0129x; 1.0033x over previous
; __device__ __forceinline__ unsigned pk2(float lo, float hi) { f32x2 v = {lo, hi}; bf16x2_t b = __builtin_convertvector(v, bf16x2_t); return __builtin_bit_cast(unsigned, b); }
;     __device__ __forceinline__ void operator()(AccT& acc, const Unit& u, int wr, int wc, int fr, int fq, LAS unsigned char*) const {
;     ...
;         const size_t tb = ((size_t)(u.pm * 12 + u.z * 4 + u.pn) * 8 + (wr * 4 + wc)) * 16; const int lane = fq * 16 + fr;
;         constexpr size_t ZSTEP = (size_t)4 * 8 * 16 * 64 * 8;
;         const bool more = (u.z < 2);
; #pragma unroll
;         for (int ai = 0; ai < 2; ++ai) {
;             u32x4 gw[8], nw[8];
; #pragma unroll
;             for (int j = 0; j < 8; ++j) { const bf16_t* gp = gates + ((tb + ai * 8 + j) * 64 + lane) * 8; gw[j] = *(const u32x4*)gp; nw[j] = *(const u32x4*)(gp + (more ? ZSTEP : 0)); }
; #pragma unroll
;             for (int m = 0; m < 4; ++m)
; #pragma unroll
;                 for (int bj = 0; bj < 2; ++bj) {
;                     f32x4 g0, g1; unpack8(gw[m * 2 + bj], g0, g1);
;                     if (more) {
;                         f32x4 h0, h1; unpack8(nw[m * 2 + bj], h0, h1);
; #pragma unroll
;                         for (int i = 0; i < 4; ++i) { acc[ai][bj][m][0][i] *= g0[i] * __builtin_amdgcn_rcpf(h0[i]); acc[ai][bj][m][1][i] *= g1[i] * __builtin_amdgcn_rcpf(h1[i]); }
;                     } else {
;                         const long off = (row0 + ai * 128 + m * 16) * 1024 + u.pn * 256 + bj * 128 + wc * 32 + 8 * fq;
;                         const f32x4 y0 = acc[ai][bj][m][0] * g0, y1 = acc[ai][bj][m][1] * g1; u32x4 w; w.x = pk2(y0.x, y0.y); w.y = pk2(y0.z, y0.w); w.z = pk2(y1.x, y1.y); w.w = pk2(y1.z, y1.w);
;                         *(u32x4*)(merged + off) = w;
;                         acc[ai][bj][m][0] = (f32x4){0.f, 0.f, 0.f, 0.f}; acc[ai][bj][m][1] = (f32x4){0.f, 0.f, 0.f, 0.f};
;                     }
.LBB0_253:
	s_lshl_b32 s1, s2, 2
	s_mul_i32 s0, s12, 12
	s_add_i32 s1, s16, s1
	s_add_i32 s0, s1, s0
	s_ashr_i32 s13, s12, 31
	s_ashr_i32 s1, s0, 31
	s_cmp_gt_i32 s2, 1
	s_cselect_b64 s[30:31], -1, 0
	s_cmp_lt_i32 s2, 2
	s_cselect_b32 s2, 0x40000, 0
	s_lshl_b64 s[0:1], s[0:1], 17
	v_lshl_add_u64 v[220:221], v[192:193], 0, s[0:1]
	s_lshl_b32 s2, s2, 1
	v_lshl_add_u64 v[106:107], v[220:221], 0, s[2:3]
	global_load_dwordx4 v[232:235], v[106:107], off
	s_mov_b64 s[0:1], 0x1000
	global_load_dwordx4 v[210:213], v[220:221], off
	global_load_dwordx4 v[182:185], v[220:221], off offset:1024
	global_load_dwordx4 v[178:181], v[106:107], off offset:1024
	global_load_dwordx4 v[174:177], v[220:221], off offset:2048
	global_load_dwordx4 v[170:173], v[106:107], off offset:2048
	global_load_dwordx4 v[166:169], v[220:221], off offset:3072
	global_load_dwordx4 v[162:165], v[106:107], off offset:3072
	v_lshl_add_u64 v[106:107], v[220:221], 0, s[0:1]
	s_movk_i32 s0, 0x1000
	v_add_co_u32_e32 v108, vcc, s0, v220
	v_lshl_add_u64 v[106:107], v[106:107], 0, s[2:3]
	s_nop 0
	v_addc_co_u32_e32 v109, vcc, 0, v221, vcc
	s_mov_b64 s[0:1], 0x1400
	global_load_dwordx4 v[158:161], v[108:109], off
	global_load_dwordx4 v[154:157], v[106:107], off
	v_lshl_add_u64 v[106:107], v[220:221], 0, s[0:1]
	v_lshl_add_u64 v[106:107], v[106:107], 0, s[2:3]
	s_mov_b64 s[0:1], 0x1800
	global_load_dwordx4 v[142:145], v[108:109], off offset:1024
	global_load_dwordx4 v[138:141], v[106:107], off
	v_lshl_add_u64 v[106:107], v[220:221], 0, s[0:1]
	v_lshl_add_u64 v[106:107], v[106:107], 0, s[2:3]
	s_mov_b64 s[0:1], 0x1c00
	global_load_dwordx4 v[126:129], v[108:109], off offset:2048
	global_load_dwordx4 v[122:125], v[106:107], off
	v_lshl_add_u64 v[106:107], v[220:221], 0, s[0:1]
	v_lshl_add_u64 v[106:107], v[106:107], 0, s[2:3]
	global_load_dwordx4 v[110:113], v[108:109], off offset:3072
	s_lshl_b64 s[0:1], s[12:13], 19
	global_load_dwordx4 v[106:109], v[106:107], off
	v_lshl_add_u64 v[218:219], s[0:1], 0, v[208:209]
	v_readlane_b32 s46, v255, 34
	s_mov_b64 s[8:9], -1
	s_and_b64 vcc, exec, s[30:31]
	v_lshl_add_u64 v[222:223], s[6:7], 0, v[218:219]
	v_lshlrev_b32_e32 v0, 1, v190
	s_mov_b64 s[78:79], 0x400
	v_readlane_b32 s47, v255, 35
	s_waitcnt vmcnt(0)
	v_lshlrev_b32_e32 v230, 16, v210
	v_and_b32_e32 v231, 0xffff0000, v210
	v_lshlrev_b32_e32 v226, 16, v211
	v_and_b32_e32 v227, 0xffff0000, v211
	v_lshlrev_b32_e32 v228, 16, v212
	v_and_b32_e32 v229, 0xffff0000, v212
	v_lshlrev_b32_e32 v224, 16, v213
	v_and_b32_e32 v225, 0xffff0000, v213
	s_cbranch_vccz .LBB0_255
	s_lshl_b32 s0, s16, 8
	s_ashr_i32 s1, s0, 31
	v_pk_mul_f32 v[204:205], v[152:153], v[226:227]
	v_pk_mul_f32 v[210:211], v[150:151], v[230:231]
	v_pk_mul_f32 v[214:215], v[148:149], v[224:225]
	v_cvt_pk_bf16_f32 v210, v210, v211
	v_cvt_pk_bf16_f32 v211, v204, v205
	v_lshl_add_u64 v[204:205], s[0:1], 1, v[222:223]
	s_lshl_b32 s0, s85, 1
	s_mov_b32 s1, s3
	v_pk_mul_f32 v[212:213], v[146:147], v[228:229]
	v_lshl_add_u64 v[204:205], v[204:205], 0, s[0:1]
	v_cvt_pk_bf16_f32 v212, v212, v213
	v_cvt_pk_bf16_f32 v213, v214, v215
	v_lshl_add_u64 v[204:205], v[204:205], 0, v[0:1]
	global_store_dwordx4 v[204:205], v[210:213], off
	s_mov_b64 s[8:9], 0
.LBB0_255:
	s_nop 0
	v_mov_b32_e32 v210, 0
	s_andn2_b64 vcc, exec, s[8:9]
	v_mov_b32_e32 v211, 0
	v_mov_b32_e32 v214, 0
	v_mov_b32_e32 v215, 0
	v_mov_b32_e32 v212, 0
	v_mov_b32_e32 v213, 0
	v_mov_b32_e32 v216, 0
	v_mov_b32_e32 v217, 0
	s_cbranch_vccnz .LBB0_257
	v_add_co_u32_e32 v204, vcc, 0x80000, v220
	s_nop 1
	v_addc_co_u32_e32 v205, vcc, 0, v221, vcc
	v_mov_b64_e32 v[210:211], v[232:233]
	v_mov_b64_e32 v[212:213], v[234:235]
	s_waitcnt vmcnt(0)
	v_lshlrev_b32_e32 v198, 16, v210
	v_and_b32_e32 v200, 0xffff0000, v210
	v_lshlrev_b32_e32 v203, 16, v212
	v_and_b32_e32 v206, 0xffff0000, v212
	v_rcp_f32_e32 v204, v198
	v_rcp_f32_e32 v205, v200
	v_lshlrev_b32_e32 v207, 16, v213
	v_and_b32_e32 v216, 0xffff0000, v213
	v_rcp_f32_e32 v212, v203
	v_rcp_f32_e32 v213, v206
	v_pk_mul_f32 v[204:205], v[204:205], v[230:231]
	v_lshlrev_b32_e32 v201, 16, v211
	v_and_b32_e32 v202, 0xffff0000, v211
	v_pk_mul_f32 v[210:211], v[150:151], v[204:205]
	v_pk_mul_f32 v[150:151], v[212:213], v[228:229]
	s_nop 0
	v_pk_mul_f32 v[212:213], v[146:147], v[150:151]
	v_rcp_f32_e32 v146, v201
	v_rcp_f32_e32 v147, v202
	v_rcp_f32_e32 v150, v207
	v_rcp_f32_e32 v151, v216
	v_pk_mul_f32 v[146:147], v[146:147], v[226:227]
	s_nop 0
	v_pk_mul_f32 v[214:215], v[152:153], v[146:147]
	v_pk_mul_f32 v[146:147], v[150:151], v[224:225]
	s_nop 0
	v_pk_mul_f32 v[216:217], v[148:149], v[146:147]

; __device__ __forceinline__ unsigned pk2(float lo, float hi) { f32x2 v = {lo, hi}; bf16x2_t b = __builtin_convertvector(v, bf16x2_t); return __builtin_bit_cast(unsigned, b); }
;     __device__ __forceinline__ void operator()(AccT& acc, const Unit& u, int wr, int wc, int fr, int fq, LAS unsigned char*) const {
;     ...
;         for (int ai = 0; ai < 2; ++ai) {
;             u32x4 gw[8], nw[8];
; #pragma unroll
;             for (int j = 0; j < 8; ++j) { const bf16_t* gp = gates + ((tb + ai * 8 + j) * 64 + lane) * 8; gw[j] = *(const u32x4*)gp; nw[j] = *(const u32x4*)(gp + (more ? ZSTEP : 0)); }
; #pragma unroll
;             for (int m = 0; m < 4; ++m)
; #pragma unroll
;                 for (int bj = 0; bj < 2; ++bj) {
;                     f32x4 g0, g1; unpack8(gw[m * 2 + bj], g0, g1);
;                     if (more) {
;                         f32x4 h0, h1; unpack8(nw[m * 2 + bj], h0, h1);
; #pragma unroll
;                         for (int i = 0; i < 4; ++i) { acc[ai][bj][m][0][i] *= g0[i] * __builtin_amdgcn_rcpf(h0[i]); acc[ai][bj][m][1][i] *= g1[i] * __builtin_amdgcn_rcpf(h1[i]); }
;                     } else {
;                         const long off = (row0 + ai * 128 + m * 16) * 1024 + u.pn * 256 + bj * 128 + wc * 32 + 8 * fq;
;                         const f32x4 y0 = acc[ai][bj][m][0] * g0, y1 = acc[ai][bj][m][1] * g1; u32x4 w; w.x = pk2(y0.x, y0.y); w.y = pk2(y0.z, y0.w); w.z = pk2(y1.x, y1.y); w.w = pk2(y1.z, y1.w);
;                         *(u32x4*)(merged + off) = w;
;                         acc[ai][bj][m][0] = (f32x4){0.f, 0.f, 0.f, 0.f}; acc[ai][bj][m][1] = (f32x4){0.f, 0.f, 0.f, 0.f};
;                     }
.LBB0_285:
	s_mov_b64 s[0:1], 0x2400
	v_add_co_u32_e32 v66, vcc, 0x2000, v220
	v_lshl_add_u64 v[68:69], v[220:221], 0, s[0:1]
	s_mov_b64 s[0:1], 0x2800
	v_addc_co_u32_e32 v67, vcc, 0, v221, vcc
	v_lshl_add_u64 v[68:69], v[68:69], 0, s[2:3]
	v_lshl_add_u64 v[70:71], v[220:221], 0, s[0:1]
	s_mov_b64 s[0:1], 0x2c00
	v_lshl_add_u64 v[240:241], v[66:67], 0, s[2:3]
	global_load_dwordx4 v[236:239], v[240:241], off
	global_load_dwordx4 v[170:173], v[66:67], off
	global_load_dwordx4 v[118:121], v[66:67], off offset:1024
	v_lshl_add_u64 v[70:71], v[70:71], 0, s[2:3]
	global_load_dwordx4 v[114:117], v[68:69], off
	global_load_dwordx4 v[106:109], v[70:71], off
	v_lshl_add_u64 v[68:69], v[220:221], 0, s[0:1]
	s_mov_b64 s[0:1], 0x3000
	global_load_dwordx4 v[110:113], v[66:67], off offset:2048
	global_load_dwordx4 v[102:105], v[66:67], off offset:3072
	v_lshl_add_u64 v[66:67], v[68:69], 0, s[2:3]
	v_lshl_add_u64 v[68:69], v[220:221], 0, s[0:1]
	s_movk_i32 s0, 0x3000
	v_add_co_u32_e32 v70, vcc, s0, v220
	s_mov_b64 s[0:1], 0x3400
	s_nop 0
	v_addc_co_u32_e32 v71, vcc, 0, v221, vcc
	global_load_dwordx4 v[98:101], v[66:67], off
	global_load_dwordx4 v[94:97], v[70:71], off
	v_lshl_add_u64 v[66:67], v[68:69], 0, s[2:3]
	v_lshl_add_u64 v[68:69], v[220:221], 0, s[0:1]
	s_mov_b64 s[0:1], 0x3800
	v_lshl_add_u64 v[68:69], v[68:69], 0, s[2:3]
	v_lshl_add_u64 v[72:73], v[220:221], 0, s[0:1]
	s_mov_b64 s[0:1], 0x3c00
	global_load_dwordx4 v[86:89], v[70:71], off offset:1024
	global_load_dwordx4 v[78:81], v[70:71], off offset:2048
	v_lshl_add_u64 v[72:73], v[72:73], 0, s[2:3]
	global_load_dwordx4 v[82:85], v[68:69], off
	global_load_dwordx4 v[74:77], v[72:73], off
	v_lshl_add_u64 v[68:69], v[220:221], 0, s[0:1]
	global_load_dwordx4 v[90:93], v[66:67], off
	s_nop 0
	global_load_dwordx4 v[70:73], v[70:71], off offset:3072
	v_lshl_add_u64 v[66:67], v[68:69], 0, s[2:3]
	global_load_dwordx4 v[66:69], v[66:67], off
	s_mov_b64 s[0:1], 0x40000
	v_lshl_add_u64 v[182:183], v[218:219], 0, s[0:1]
	s_mov_b64 s[8:9], -1
	s_and_b64 vcc, exec, s[40:41]
	v_lshl_add_u64 v[222:223], s[6:7], 0, v[182:183]
	s_waitcnt vmcnt(14)
	v_lshlrev_b32_e32 v230, 16, v170
	v_and_b32_e32 v231, 0xffff0000, v170
	v_lshlrev_b32_e32 v226, 16, v171
	v_and_b32_e32 v227, 0xffff0000, v171
	v_lshlrev_b32_e32 v228, 16, v172
	v_and_b32_e32 v229, 0xffff0000, v172
	v_lshlrev_b32_e32 v224, 16, v173
	v_and_b32_e32 v225, 0xffff0000, v173
	s_cbranch_vccnz .LBB0_287
	s_lshl_b32 s0, s16, 8
	s_ashr_i32 s1, s0, 31
	v_pk_mul_f32 v[172:173], v[64:65], v[226:227]
	v_pk_mul_f32 v[170:171], v[62:63], v[230:231]
	v_pk_mul_f32 v[182:183], v[60:61], v[224:225]
	v_cvt_pk_bf16_f32 v170, v170, v171
	v_cvt_pk_bf16_f32 v171, v172, v173
	v_cvt_pk_bf16_f32 v173, v182, v183
	v_lshl_add_u64 v[182:183], s[0:1], 1, v[222:223]
	s_lshl_b32 s2, s85, 1
	v_pk_mul_f32 v[184:185], v[58:59], v[228:229]
	v_lshl_add_u64 v[182:183], v[182:183], 0, s[2:3]
	v_cvt_pk_bf16_f32 v172, v184, v185
	v_lshl_add_u64 v[182:183], v[182:183], 0, v[0:1]
	s_mov_b64 s[8:9], 0
	global_store_dwordx4 v[182:183], v[170:173], off
.LBB0_287:
	s_nop 1
	v_mov_b32_e32 v172, 0
	s_andn2_b64 vcc, exec, s[8:9]
	v_mov_b32_e32 v173, 0
	v_mov_b32_e32 v184, 0
	v_mov_b32_e32 v185, 0
	v_mov_b32_e32 v170, 0
	v_mov_b32_e32 v171, 0
	v_mov_b32_e32 v182, 0
	v_mov_b32_e32 v183, 0
	s_cbranch_vccnz .LBB0_289
	v_add_co_u32_e32 v170, vcc, 0x82000, v220
	s_nop 1
	v_addc_co_u32_e32 v171, vcc, 0, v221, vcc
	v_mov_b64_e32 v[170:171], v[236:237]
	v_mov_b64_e32 v[172:173], v[238:239]
	s_waitcnt vmcnt(0)
	v_lshlrev_b32_e32 v182, 16, v170
	v_and_b32_e32 v183, 0xffff0000, v170
	v_lshlrev_b32_e32 v184, 16, v171
	v_and_b32_e32 v185, 0xffff0000, v171
	v_lshlrev_b32_e32 v171, 16, v172
	v_and_b32_e32 v198, 0xffff0000, v172
	v_rcp_f32_e32 v170, v182
	v_rcp_f32_e32 v172, v171
	v_rcp_f32_e32 v171, v183
	v_lshlrev_b32_e32 v200, 16, v173
	v_and_b32_e32 v201, 0xffff0000, v173
	v_rcp_f32_e32 v173, v198
	v_pk_mul_f32 v[170:171], v[170:171], v[230:231]
	s_nop 0
	v_pk_mul_f32 v[170:171], v[62:63], v[170:171]
	v_pk_mul_f32 v[62:63], v[172:173], v[228:229]
	s_nop 0
	v_pk_mul_f32 v[172:173], v[58:59], v[62:63]
	v_rcp_f32_e32 v58, v184
	v_rcp_f32_e32 v59, v185
	v_rcp_f32_e32 v62, v200
	v_rcp_f32_e32 v63, v201
	v_pk_mul_f32 v[58:59], v[58:59], v[226:227]
	s_nop 0
	v_pk_mul_f32 v[182:183], v[64:65], v[58:59]
	v_pk_mul_f32 v[58:59], v[62:63], v[224:225]
	s_nop 0
	v_pk_mul_f32 v[184:185], v[60:61], v[58:59]

; template <int NP> __device__ __forceinline__ void row_scales(float (&rs)[2][4], const float* base, long row0, int fq, float inv_n) {
;     float t[2][4];
; #pragma unroll
;     for (int ai = 0; ai < 2; ++ai)
; #pragma unroll
;         for (int m = 0; m < 4; ++m) { const long row = row0 + ai * 128 + m * 16;
;             if (NP == 16) { const f32x4 v = *(const f32x4*)(base + row * 16 + 4 * fq); t[ai][m] = (v.x + v.y) + (v.z + v.w); }
;             else if (NP == 8) { const f32x2 v = *(const f32x2*)(base + row * 8 + 2 * fq); t[ai][m] = v.x + v.y; }
;             else t[ai][m] = base[row * 4 + fq]; }
; #pragma unroll
;     for (int ai = 0; ai < 2; ++ai)
; #pragma unroll
;         for (int m = 0; m < 4; ++m) rs[ai][m] = rsqrtf(red_fq(t[ai][m]) * inv_n + EPS);
;     __device__ __forceinline__ void operator()(AccT& acc, const Unit& u, int wr, int wc, int fr, int fq, LAS unsigned char*) const {
;         const long row0 = (long)u.pm * 256 + wr * 64 + fr;
;         float rsa[2][4]; row_scales<8>(rsa, ssq_cq, row0, fq, 1.f / 384.f);
.LBB0_462:
	s_ashr_i32 s13, s12, 31
	s_lshl_b64 s[0:1], s[12:13], 8
	v_lshl_add_u64 v[208:209], s[0:1], 0, v[176:177]
	v_lshlrev_b64 v[130:131], 5, v[208:209]
	v_lshl_add_u64 v[130:131], v[180:181], 0, v[130:131]
	global_load_dwordx2 v[132:133], v[130:131], off
	v_add_co_u32_e32 v146, vcc, 0x1000, v130
	s_nop 1
	v_addc_co_u32_e32 v147, vcc, 0, v131, vcc
	global_load_dwordx2 v[148:149], v[130:131], off offset:512
	global_load_dwordx2 v[150:151], v[130:131], off offset:1024
	global_load_dwordx2 v[152:153], v[130:131], off offset:1536
	global_load_dwordx2 v[154:155], v[146:147], off
	global_load_dwordx2 v[156:157], v[146:147], off offset:512
	global_load_dwordx2 v[158:159], v[146:147], off offset:1024
	global_load_dwordx2 v[160:161], v[146:147], off offset:1536
	s_mov_b32 s0, 0x358637bd
	s_mov_b32 s8, 0x3b2aaaab
	s_cmp_lg_u32 s89, 0
	v_lshlrev_b64 v[224:225], 4, v[208:209]
	s_waitcnt vmcnt(0)
	v_pk_add_f32 v[134:135], v[132:133], v[132:133] op_sel:[0,1] op_sel_hi:[1,0]
	v_mov_b64_e32 v[132:133], v[148:149]
	v_mov_b32_e32 v0, v134
	s_nop 1
	v_permlane16_swap_b32_e32 v134, v0
	v_add_f32_e32 v135, v134, v0
	v_pk_add_f32 v[142:143], v[132:133], v[132:133] op_sel:[0,1] op_sel_hi:[1,0]
	v_mov_b64_e32 v[132:133], v[150:151]
	v_mov_b32_e32 v0, v142
	s_nop 1
	v_permlane16_swap_b32_e32 v142, v0
	v_add_f32_e32 v134, v142, v0
	v_mov_b32_e32 v143, v135
	v_mov_b32_e32 v142, v134
	s_nop 0
	v_permlane32_swap_b32_e32 v135, v143
	v_permlane32_swap_b32_e32 v134, v142
	v_pk_add_f32 v[142:143], v[134:135], v[142:143]
	v_mov_b64_e32 v[134:135], s[0:1]
	v_pk_fma_f32 v[142:143], v[142:143], s[8:9], v[134:135] op_sel_hi:[1,0,0]
	v_pk_add_f32 v[144:145], v[132:133], v[132:133] op_sel:[0,1] op_sel_hi:[1,0]
	v_mov_b64_e32 v[132:133], v[152:153]
	v_add_co_u32_e32 v130, vcc, 0x1000, v130
	v_mul_f32_e32 v0, 0x4b800000, v143
	s_nop 0
	v_addc_co_u32_e32 v131, vcc, 0, v131, vcc
	v_cmp_gt_f32_e64 s[0:1], s33, v143
	v_cmp_gt_f32_e32 vcc, s33, v142
	v_pk_add_f32 v[140:141], v[132:133], v[132:133] op_sel:[0,1] op_sel_hi:[1,0]
	v_mov_b64_e32 v[132:133], v[154:155]
	v_cndmask_b32_e64 v0, v143, v0, s[0:1]
	v_rsq_f32_e32 v0, v0
	v_pk_add_f32 v[138:139], v[132:133], v[132:133] op_sel:[0,1] op_sel_hi:[1,0]
	v_mov_b64_e32 v[132:133], v[156:157]
	v_pk_add_f32 v[136:137], v[132:133], v[132:133] op_sel:[0,1] op_sel_hi:[1,0]
	v_mov_b64_e32 v[132:133], v[158:159]
	v_pk_add_f32 v[132:133], v[132:133], v[132:133] op_sel:[0,1] op_sel_hi:[1,0]
	v_mov_b64_e32 v[130:131], v[160:161]
	v_pk_add_f32 v[130:131], v[130:131], v[130:131] op_sel:[0,1] op_sel_hi:[1,0]
	s_nop 0
	v_mul_f32_e32 v131, 0x45800000, v0
	v_cndmask_b32_e64 v222, v0, v131, s[0:1]
	v_mul_f32_e32 v0, 0x4b800000, v142
	v_cndmask_b32_e32 v0, v142, v0, vcc
	v_rsq_f32_e32 v0, v0
	s_nop 0
	v_mul_f32_e32 v131, 0x45800000, v0
	v_cndmask_b32_e32 v214, v0, v131, vcc
	v_mov_b32_e32 v0, v144
	s_nop 1
	v_permlane16_swap_b32_e32 v144, v0
	v_add_f32_e32 v141, v144, v0
	v_mov_b32_e32 v0, v140
	s_nop 1
	v_permlane16_swap_b32_e32 v140, v0
	v_add_f32_e32 v140, v140, v0
	v_mov_b32_e32 v143, v141
	v_mov_b32_e32 v142, v140
	s_nop 0
	v_permlane32_swap_b32_e32 v141, v143
	v_permlane32_swap_b32_e32 v140, v142
	v_pk_add_f32 v[140:141], v[140:141], v[142:143]
	s_nop 0
	v_pk_fma_f32 v[140:141], v[140:141], s[8:9], v[134:135] op_sel_hi:[1,0,0]
	s_nop 0
	v_mul_f32_e32 v0, 0x4b800000, v141
	v_cmp_gt_f32_e64 s[0:1], s33, v141
	v_cmp_gt_f32_e32 vcc, s33, v140
	s_nop 0
	v_cndmask_b32_e64 v0, v141, v0, s[0:1]
	v_rsq_f32_e32 v0, v0
	s_nop 0
	v_mul_f32_e32 v131, 0x45800000, v0
	v_cndmask_b32_e64 v216, v0, v131, s[0:1]
	v_mul_f32_e32 v0, 0x4b800000, v140
	v_cndmask_b32_e32 v0, v140, v0, vcc
	v_rsq_f32_e32 v0, v0
	s_nop 0
	v_mul_f32_e32 v131, 0x45800000, v0
	v_cndmask_b32_e32 v210, v0, v131, vcc
	v_mov_b32_e32 v0, v138
	s_nop 1
	v_permlane16_swap_b32_e32 v138, v0
	v_add_f32_e32 v137, v138, v0
	v_mov_b32_e32 v0, v136
	s_nop 1
	v_permlane16_swap_b32_e32 v136, v0
	v_add_f32_e32 v136, v136, v0
	v_mov_b32_e32 v139, v137
	v_mov_b32_e32 v138, v136
	s_nop 0
	v_permlane32_swap_b32_e32 v137, v139
	v_permlane32_swap_b32_e32 v136, v138
	v_pk_add_f32 v[136:137], v[136:137], v[138:139]
	s_nop 0
	v_pk_fma_f32 v[136:137], v[136:137], s[8:9], v[134:135] op_sel_hi:[1,0,0]
	s_nop 0
	v_mul_f32_e32 v0, 0x4b800000, v137
	v_cmp_gt_f32_e64 s[0:1], s33, v137
	v_cmp_gt_f32_e32 vcc, s33, v136
	s_nop 0
	v_cndmask_b32_e64 v0, v137, v0, s[0:1]
	v_rsq_f32_e32 v0, v0
	s_nop 0
	v_mul_f32_e32 v131, 0x45800000, v0
	v_cndmask_b32_e64 v220, v0, v131, s[0:1]
	v_mul_f32_e32 v0, 0x4b800000, v136
	v_cndmask_b32_e32 v0, v136, v0, vcc
	v_rsq_f32_e32 v0, v0
	s_nop 0
	v_mul_f32_e32 v131, 0x45800000, v0
	v_cndmask_b32_e32 v218, v0, v131, vcc
	v_mov_b32_e32 v0, v132
	s_nop 1
	v_permlane16_swap_b32_e32 v132, v0
	v_add_f32_e32 v131, v132, v0
	v_mov_b32_e32 v0, v130
	s_nop 1
	v_permlane16_swap_b32_e32 v130, v0
	v_add_f32_e32 v130, v130, v0
	v_mov_b32_e32 v133, v131
	v_mov_b32_e32 v132, v130
	s_nop 0
	v_permlane32_swap_b32_e32 v131, v133
	v_permlane32_swap_b32_e32 v130, v132
	v_pk_add_f32 v[130:131], v[130:131], v[132:133]
	s_nop 0
	v_pk_fma_f32 v[130:131], v[130:131], s[8:9], v[134:135] op_sel_hi:[1,0,0]
	s_nop 0
	v_mul_f32_e32 v0, 0x4b800000, v131
	v_cmp_gt_f32_e64 s[0:1], s33, v131
	v_cmp_gt_f32_e32 vcc, s33, v130
	s_nop 0
	v_cndmask_b32_e64 v0, v131, v0, s[0:1]
	v_rsq_f32_e32 v0, v0
	s_nop 0
	v_mul_f32_e32 v131, 0x45800000, v0
	v_cndmask_b32_e64 v212, v0, v131, s[0:1]
	v_mul_f32_e32 v0, 0x4b800000, v130
	v_cndmask_b32_e32 v0, v130, v0, vcc
	v_rsq_f32_e32 v0, v0
	s_nop 0
	v_mul_f32_e32 v130, 0x45800000, v0
	v_cndmask_b32_e32 v198, v0, v130, vcc
	s_cbranch_scc0 .LBB0_497
; __device__ __forceinline__ float dot4(f32x4 a) { return (a.x * a.x + a.y * a.y) + (a.z * a.z + a.w * a.w); }
;     __device__ __forceinline__ void operator()(AccT& acc, const Unit& u, int wr, int wc, int fr, int fq, LAS unsigned char*) const {
;     ...
;             const f32x4 g1 = *(const f32x4*)(gq + 64 + 4 * fq), g2 = *(const f32x4*)(gq + 80 + 4 * fq);
; #pragma unroll
;             for (int ai = 0; ai < 2; ++ai) {
;                 f32x4 cs[4], sn[4];
; #pragma unroll
;                 for (int m = 0; m < 4; ++m) { const long row = row0 + ai * 128 + m * 16; cs[m] = *(const f32x4*)(cosT + row * 16 + 4 * fq); sn[m] = *(const f32x4*)(sinT + row * 16 + 4 * fq); }
; #pragma unroll
;                 for (int m = 0; m < 4; ++m) { const long row = row0 + ai * 128 + m * 16; const float rs = rsa[ai][m];
;                     const f32x4 x1 = acc[ai][0][m][0] * rs, x2 = acc[ai][0][m][1] * rs;
;                     float ss = red_fq(dot4(x1) + dot4(x2)); if (fq == 0) ssq_qr[row * 4 + wc] = ss;
	v_lshlrev_b64 v[138:139], 6, v[208:209]
	v_lshl_add_u64 v[140:141], v[184:185], 0, v[138:139]
	v_lshl_add_u64 v[138:139], v[186:187], 0, v[138:139]
	v_or_b32_e32 v230, 16, v208
	v_mov_b32_e32 v231, v209
	global_load_dwordx4 v[134:137], v[182:183], off offset:256
	global_load_dwordx4 v[130:133], v[182:183], off offset:320
	global_load_dwordx4 v[162:165], v[140:141], off
	global_load_dwordx4 v[166:169], v[138:139], off
	v_lshlrev_b64 v[138:139], 6, v[230:231]
	v_lshl_add_u64 v[140:141], v[184:185], 0, v[138:139]
	v_lshl_add_u64 v[138:139], v[186:187], 0, v[138:139]
	v_or_b32_e32 v228, 32, v208
	v_mov_b32_e32 v229, v209
	global_load_dwordx4 v[154:157], v[140:141], off
	global_load_dwordx4 v[158:161], v[138:139], off
	v_lshlrev_b64 v[138:139], 6, v[228:229]
	v_lshl_add_u64 v[140:141], v[184:185], 0, v[138:139]
	v_lshl_add_u64 v[138:139], v[186:187], 0, v[138:139]
	v_or_b32_e32 v226, 48, v208
	v_mov_b32_e32 v227, v209
	global_load_dwordx4 v[146:149], v[140:141], off
	global_load_dwordx4 v[150:153], v[138:139], off
	v_lshlrev_b64 v[138:139], 6, v[226:227]
	v_lshl_add_u64 v[140:141], v[184:185], 0, v[138:139]
	v_lshl_add_u64 v[142:143], v[186:187], 0, v[138:139]
	global_load_dwordx4 v[138:141], v[140:141], off
	s_nop 0
	global_load_dwordx4 v[142:145], v[142:143], off
	v_pk_mul_f32 v[236:237], v[128:129], v[222:223] op_sel_hi:[1,0]
	v_pk_mul_f32 v[238:239], v[126:127], v[222:223] op_sel_hi:[1,0]
	v_mul_f32_e32 v197, v237, v237
	v_mul_f32_e32 v0, v239, v239
	v_pk_mul_f32 v[232:233], v[124:125], v[222:223] op_sel_hi:[1,0]
	v_pk_mul_f32 v[234:235], v[122:123], v[222:223] op_sel_hi:[1,0]
	v_fmac_f32_e32 v0, v238, v238
	v_fmac_f32_e32 v197, v236, v236
	v_add_f32_e32 v0, v0, v197
	v_mul_f32_e32 v197, v235, v235
	v_mul_f32_e32 v200, v233, v233
	v_fmac_f32_e32 v197, v234, v234
	v_fmac_f32_e32 v200, v232, v232
	v_add_f32_e32 v197, v197, v200
	v_add_f32_e32 v0, v0, v197
	v_mov_b32_e32 v197, v0
	s_nop 1
	v_permlane16_swap_b32_e32 v0, v197
	v_add_f32_e32 v0, v0, v197
	v_mov_b32_e32 v197, v0
	s_nop 1
	v_permlane32_swap_b32_e32 v0, v197
	s_and_saveexec_b64 s[0:1], s[40:41]
	s_mov_b64 s[12:13], 0x3000
	s_cbranch_execz .LBB0_465
	v_lshl_add_u64 v[204:205], s[68:69], 0, v[224:225]
	v_add_f32_e32 v0, v0, v197
	global_store_dword v[204:205], v0, off

; #define LAS __attribute__((address_space(3)))
; __device__ __forceinline__ void wconv_item(LAS float* scr, const WEnt& e, int item, int lane) {
;     const int nblk = e.Np / 32, kb = item / nblk, nb = item % nblk, k0 = 64 * kb, n0 = 32 * nb;
;     const int col = colmap(e.cm, n0 + (lane & 31));
;     const float* sp = e.src + (size_t)(k0 + (lane >> 5)) * e.src_ld + (col >= 0 ? col : 0);
;     const float* gp = e.gain ? e.gain + k0 + (lane >> 5) : nullptr;
;     float vv[32];
; #pragma unroll
;     for (int i = 0; i < 32; ++i) vv[i] = sp[(size_t)(2 * i) * e.src_ld];
; #pragma unroll
;     for (int i = 0; i < 32; ++i) { float v = vv[i]; if (gp) v *= gp[2 * i]; scr[(2 * i + (lane >> 5)) * 33 + (lane & 31)] = (col >= 0) ? v : 0.f; }
.LBB0_1167:
	s_or_b64 exec, exec, s[30:31]
	v_lshlrev_b32_e32 v18, 6, v18
	v_or_b32_e32 v0, v18, v4
	v_ashrrev_i32_e32 v19, 31, v18
	v_lshl_add_u64 v[98:99], v[18:19], 2, v[12:13]
	v_lshlrev_b32_e32 v100, 2, v4
	v_mov_b32_e32 v101, 0
	v_cmp_ne_u64_e32 vcc, 0, v[12:13]
	v_lshl_add_u64 v[98:99], v[98:99], 0, v[100:101]
	s_and_saveexec_b64 s[8:9], vcc
	s_cbranch_execz .Lwconv_nogain
	global_load_dword v66, v[98:99], off
	global_load_dword v67, v[98:99], off offset:8
	global_load_dword v68, v[98:99], off offset:16
	global_load_dword v69, v[98:99], off offset:24
	global_load_dword v70, v[98:99], off offset:32
	global_load_dword v71, v[98:99], off offset:40
	global_load_dword v72, v[98:99], off offset:48
	global_load_dword v73, v[98:99], off offset:56
	global_load_dword v74, v[98:99], off offset:64
	global_load_dword v75, v[98:99], off offset:72
	global_load_dword v76, v[98:99], off offset:80
	global_load_dword v77, v[98:99], off offset:88
	global_load_dword v78, v[98:99], off offset:96
	global_load_dword v79, v[98:99], off offset:104
	global_load_dword v80, v[98:99], off offset:112
	global_load_dword v81, v[98:99], off offset:120
	global_load_dword v82, v[98:99], off offset:128
	global_load_dword v83, v[98:99], off offset:136
	global_load_dword v84, v[98:99], off offset:144
	global_load_dword v85, v[98:99], off offset:152
	global_load_dword v86, v[98:99], off offset:160
	global_load_dword v87, v[98:99], off offset:168
	global_load_dword v88, v[98:99], off offset:176
	global_load_dword v89, v[98:99], off offset:184
	global_load_dword v90, v[98:99], off offset:192
	global_load_dword v91, v[98:99], off offset:200
	global_load_dword v92, v[98:99], off offset:208
	global_load_dword v93, v[98:99], off offset:216
	global_load_dword v94, v[98:99], off offset:224
	global_load_dword v95, v[98:99], off offset:232
	global_load_dword v96, v[98:99], off offset:240
	global_load_dword v97, v[98:99], off offset:248
.Lwconv_nogain:
	s_or_b64 exec, exec, s[8:9]
	v_mul_lo_u32 v36, v16, v19
	v_mul_lo_u32 v37, v17, v0
	v_mad_u64_u32 v[34:35], s[8:9], v16, v0, 0
	v_add3_u32 v35, v35, v36, v37
	v_cmp_lt_i32_e32 vcc, -1, v7
	v_lshl_add_u64 v[14:15], v[34:35], 2, v[14:15]
	v_lshlrev_b64 v[64:65], 3, v[16:17]
	v_cndmask_b32_e32 v0, 0, v7, vcc
	v_lshl_add_u64 v[14:15], v[0:1], 2, v[14:15]
	v_lshl_add_u64 v[16:17], v[14:15], 0, v[64:65]
	v_lshl_add_u64 v[34:35], v[16:17], 0, v[64:65]
	v_lshl_add_u64 v[36:37], v[34:35], 0, v[64:65]
	v_lshl_add_u64 v[38:39], v[36:37], 0, v[64:65]
	v_lshl_add_u64 v[40:41], v[38:39], 0, v[64:65]
	v_lshl_add_u64 v[42:43], v[40:41], 0, v[64:65]
	v_lshl_add_u64 v[44:45], v[42:43], 0, v[64:65]
	global_load_dword v62, v[14:15], off
	global_load_dword v61, v[16:17], off
	global_load_dword v60, v[34:35], off
	global_load_dword v59, v[36:37], off
	global_load_dword v58, v[38:39], off
	global_load_dword v57, v[40:41], off
	global_load_dword v56, v[42:43], off
	global_load_dword v55, v[44:45], off
	v_lshl_add_u64 v[14:15], v[44:45], 0, v[64:65]
	global_load_dword v54, v[14:15], off
	v_lshl_add_u64 v[14:15], v[14:15], 0, v[64:65]
	global_load_dword v53, v[14:15], off
	v_lshl_add_u64 v[14:15], v[14:15], 0, v[64:65]
	global_load_dword v52, v[14:15], off
	v_lshl_add_u64 v[14:15], v[14:15], 0, v[64:65]
	global_load_dword v51, v[14:15], off
	v_lshl_add_u64 v[14:15], v[14:15], 0, v[64:65]
	global_load_dword v50, v[14:15], off
	v_lshl_add_u64 v[14:15], v[14:15], 0, v[64:65]
	global_load_dword v49, v[14:15], off
	v_lshl_add_u64 v[14:15], v[14:15], 0, v[64:65]
	global_load_dword v48, v[14:15], off
	v_lshl_add_u64 v[14:15], v[14:15], 0, v[64:65]
	global_load_dword v47, v[14:15], off
	v_lshl_add_u64 v[14:15], v[14:15], 0, v[64:65]
	global_load_dword v46, v[14:15], off
	v_lshl_add_u64 v[14:15], v[14:15], 0, v[64:65]
	global_load_dword v45, v[14:15], off
	v_lshl_add_u64 v[14:15], v[14:15], 0, v[64:65]
	global_load_dword v44, v[14:15], off
	v_lshl_add_u64 v[14:15], v[14:15], 0, v[64:65]
	global_load_dword v43, v[14:15], off
	v_lshl_add_u64 v[14:15], v[14:15], 0, v[64:65]
	global_load_dword v42, v[14:15], off
	v_lshl_add_u64 v[14:15], v[14:15], 0, v[64:65]
	global_load_dword v41, v[14:15], off
	v_lshl_add_u64 v[14:15], v[14:15], 0, v[64:65]
	global_load_dword v40, v[14:15], off
	v_lshl_add_u64 v[14:15], v[14:15], 0, v[64:65]
	global_load_dword v39, v[14:15], off
	v_lshl_add_u64 v[14:15], v[14:15], 0, v[64:65]
	global_load_dword v38, v[14:15], off
	v_lshl_add_u64 v[14:15], v[14:15], 0, v[64:65]
	global_load_dword v37, v[14:15], off
	v_lshl_add_u64 v[14:15], v[14:15], 0, v[64:65]
	global_load_dword v36, v[14:15], off
	v_lshl_add_u64 v[14:15], v[14:15], 0, v[64:65]
	global_load_dword v35, v[14:15], off
	v_lshl_add_u64 v[14:15], v[14:15], 0, v[64:65]
	global_load_dword v34, v[14:15], off
	v_lshl_add_u64 v[14:15], v[14:15], 0, v[64:65]
	global_load_dword v17, v[14:15], off
	v_lshl_add_u64 v[14:15], v[14:15], 0, v[64:65]
	global_load_dword v16, v[14:15], off
	v_lshl_add_u64 v[14:15], v[14:15], 0, v[64:65]
	global_load_dword v7, v[14:15], off
	v_lshl_add_u64 v[14:15], v[18:19], 2, v[12:13]
	v_lshlrev_b32_e32 v0, 2, v4
	v_lshl_add_u64 v[14:15], v[14:15], 0, v[0:1]
	v_cmp_ne_u64_e64 s[38:39], 0, v[12:13]
	s_and_saveexec_b64 s[8:9], s[38:39]
	s_xor_b64 s[8:9], exec, s[8:9]
	s_cbranch_execz .LBB0_1169
	s_waitcnt vmcnt(31)
	v_mul_f32_e32 v0, v62, v66
	v_cndmask_b32_e32 v0, 0, v0, vcc
	s_waitcnt vmcnt(30)
	v_mul_f32_e32 v61, v61, v67

; __device__ __forceinline__ void wconv_item(LAS float* scr, const WEnt& e, int item, int lane) {
;     ...
;     for (int i = 0; i < 32; ++i) vv[i] = sp[(size_t)(2 * i) * e.src_ld];
; #pragma unroll
;     for (int i = 0; i < 32; ++i) { float v = vv[i]; if (gp) v *= gp[2 * i]; scr[(2 * i + (lane >> 5)) * 33 + (lane & 31)] = (col >= 0) ? v : 0.f; }
.LBB0_1171:
	s_or_b64 exec, exec, s[8:9]
	s_waitcnt vmcnt(30)
	v_cndmask_b32_e32 v12, 0, v61, vcc
	ds_write2_b32 v32, v0, v12 offset1:66
	s_and_saveexec_b64 s[8:9], s[38:39]
	s_xor_b64 s[8:9], exec, s[8:9]
	s_cbranch_execz .LBB0_1173
	s_waitcnt vmcnt(29)
	v_mul_f32_e32 v0, v60, v68
	v_cndmask_b32_e32 v0, 0, v0, vcc
	s_waitcnt vmcnt(28)
	v_mul_f32_e32 v59, v59, v69

; __device__ __forceinline__ void wconv_item(LAS float* scr, const WEnt& e, int item, int lane) {
;     ...
;     for (int i = 0; i < 32; ++i) vv[i] = sp[(size_t)(2 * i) * e.src_ld];
; #pragma unroll
;     for (int i = 0; i < 32; ++i) { float v = vv[i]; if (gp) v *= gp[2 * i]; scr[(2 * i + (lane >> 5)) * 33 + (lane & 31)] = (col >= 0) ? v : 0.f; }
.LBB0_1175:
	s_or_b64 exec, exec, s[8:9]
	s_waitcnt vmcnt(28)
	v_cndmask_b32_e32 v12, 0, v59, vcc
	ds_write2_b32 v32, v0, v12 offset0:132 offset1:198
	s_and_saveexec_b64 s[8:9], s[38:39]
	s_xor_b64 s[8:9], exec, s[8:9]
	s_cbranch_execz .LBB0_1177
	s_waitcnt vmcnt(27)
	v_mul_f32_e32 v0, v58, v70
	v_cndmask_b32_e32 v12, 0, v0, vcc
	s_waitcnt vmcnt(26)
	v_mul_f32_e32 v57, v57, v71

; __device__ __forceinline__ void wconv_item(LAS float* scr, const WEnt& e, int item, int lane) {
;     ...
;     for (int i = 0; i < 32; ++i) vv[i] = sp[(size_t)(2 * i) * e.src_ld];
; #pragma unroll
;     for (int i = 0; i < 32; ++i) { float v = vv[i]; if (gp) v *= gp[2 * i]; scr[(2 * i + (lane >> 5)) * 33 + (lane & 31)] = (col >= 0) ? v : 0.f; }
.LBB0_1179:
	s_or_b64 exec, exec, s[8:9]
	s_waitcnt vmcnt(26)
	v_cndmask_b32_e32 v13, 0, v57, vcc
	v_add_u32_e32 v0, 0x400, v32
	ds_write2_b32 v0, v12, v13 offset0:8 offset1:74
	s_and_saveexec_b64 s[8:9], s[38:39]
	s_xor_b64 s[8:9], exec, s[8:9]
	s_cbranch_execz .LBB0_1181
	s_waitcnt vmcnt(25)
	v_mul_f32_e32 v12, v56, v72
	v_cndmask_b32_e32 v12, 0, v12, vcc
	s_waitcnt vmcnt(24)
	v_mul_f32_e32 v55, v55, v73

; __device__ __forceinline__ void wconv_item(LAS float* scr, const WEnt& e, int item, int lane) {
;     ...
;     for (int i = 0; i < 32; ++i) vv[i] = sp[(size_t)(2 * i) * e.src_ld];
; #pragma unroll
;     for (int i = 0; i < 32; ++i) { float v = vv[i]; if (gp) v *= gp[2 * i]; scr[(2 * i + (lane >> 5)) * 33 + (lane & 31)] = (col >= 0) ? v : 0.f; }
.LBB0_1183:
	s_or_b64 exec, exec, s[8:9]
	s_waitcnt vmcnt(24)
	v_cndmask_b32_e32 v13, 0, v55, vcc
	ds_write2_b32 v0, v12, v13 offset0:140 offset1:206
	s_and_saveexec_b64 s[8:9], s[38:39]
	s_xor_b64 s[8:9], exec, s[8:9]
	s_cbranch_execz .LBB0_1185
	s_waitcnt vmcnt(23)
	v_mul_f32_e32 v0, v54, v74
	v_cndmask_b32_e32 v12, 0, v0, vcc
	s_waitcnt vmcnt(22)
	v_mul_f32_e32 v53, v53, v75

; __device__ __forceinline__ void wconv_item(LAS float* scr, const WEnt& e, int item, int lane) {
;     ...
;     for (int i = 0; i < 32; ++i) vv[i] = sp[(size_t)(2 * i) * e.src_ld];
; #pragma unroll
;     for (int i = 0; i < 32; ++i) { float v = vv[i]; if (gp) v *= gp[2 * i]; scr[(2 * i + (lane >> 5)) * 33 + (lane & 31)] = (col >= 0) ? v : 0.f; }
.LBB0_1187:
	s_or_b64 exec, exec, s[8:9]
	s_waitcnt vmcnt(22)
	v_cndmask_b32_e32 v13, 0, v53, vcc
	v_add_u32_e32 v0, 0x800, v32
	ds_write2_b32 v0, v12, v13 offset0:16 offset1:82
	s_and_saveexec_b64 s[8:9], s[38:39]
	s_xor_b64 s[8:9], exec, s[8:9]
	s_cbranch_execz .LBB0_1189
	s_waitcnt vmcnt(21)
	v_mul_f32_e32 v12, v52, v76
	v_cndmask_b32_e32 v12, 0, v12, vcc
	s_waitcnt vmcnt(20)
	v_mul_f32_e32 v51, v51, v77

; __device__ __forceinline__ void wconv_item(LAS float* scr, const WEnt& e, int item, int lane) {
;     ...
;     for (int i = 0; i < 32; ++i) vv[i] = sp[(size_t)(2 * i) * e.src_ld];
; #pragma unroll
;     for (int i = 0; i < 32; ++i) { float v = vv[i]; if (gp) v *= gp[2 * i]; scr[(2 * i + (lane >> 5)) * 33 + (lane & 31)] = (col >= 0) ? v : 0.f; }
.LBB0_1191:
	s_or_b64 exec, exec, s[8:9]
	s_waitcnt vmcnt(20)
	v_cndmask_b32_e32 v13, 0, v51, vcc
	ds_write2_b32 v0, v12, v13 offset0:148 offset1:214
	s_and_saveexec_b64 s[8:9], s[38:39]
	s_xor_b64 s[8:9], exec, s[8:9]
	s_cbranch_execz .LBB0_1193
	s_waitcnt vmcnt(19)
	v_mul_f32_e32 v0, v50, v78
	v_cndmask_b32_e32 v12, 0, v0, vcc
	s_waitcnt vmcnt(18)
	v_mul_f32_e32 v49, v49, v79

; __device__ __forceinline__ void wconv_item(LAS float* scr, const WEnt& e, int item, int lane) {
;     ...
;     for (int i = 0; i < 32; ++i) vv[i] = sp[(size_t)(2 * i) * e.src_ld];
; #pragma unroll
;     for (int i = 0; i < 32; ++i) { float v = vv[i]; if (gp) v *= gp[2 * i]; scr[(2 * i + (lane >> 5)) * 33 + (lane & 31)] = (col >= 0) ? v : 0.f; }
.LBB0_1195:
	s_or_b64 exec, exec, s[8:9]
	s_waitcnt vmcnt(18)
	v_cndmask_b32_e32 v13, 0, v49, vcc
	v_add_u32_e32 v0, 0xc00, v32
	ds_write2_b32 v0, v12, v13 offset0:24 offset1:90
	s_and_saveexec_b64 s[8:9], s[38:39]
	s_xor_b64 s[8:9], exec, s[8:9]
	s_cbranch_execz .LBB0_1197
	s_waitcnt vmcnt(17)
	v_mul_f32_e32 v12, v48, v80
	v_cndmask_b32_e32 v12, 0, v12, vcc
	s_waitcnt vmcnt(16)
	v_mul_f32_e32 v47, v47, v81

; __device__ __forceinline__ void wconv_item(LAS float* scr, const WEnt& e, int item, int lane) {
;     ...
;     for (int i = 0; i < 32; ++i) vv[i] = sp[(size_t)(2 * i) * e.src_ld];
; #pragma unroll
;     for (int i = 0; i < 32; ++i) { float v = vv[i]; if (gp) v *= gp[2 * i]; scr[(2 * i + (lane >> 5)) * 33 + (lane & 31)] = (col >= 0) ? v : 0.f; }
.LBB0_1199:
	s_or_b64 exec, exec, s[8:9]
	s_waitcnt vmcnt(16)
	v_cndmask_b32_e32 v13, 0, v47, vcc
	ds_write2_b32 v0, v12, v13 offset0:156 offset1:222
	s_and_saveexec_b64 s[8:9], s[38:39]
	s_xor_b64 s[8:9], exec, s[8:9]
	s_cbranch_execz .LBB0_1201
	s_waitcnt vmcnt(15)
	v_mul_f32_e32 v0, v46, v82
	v_cndmask_b32_e32 v12, 0, v0, vcc
	s_waitcnt vmcnt(14)
	v_mul_f32_e32 v45, v45, v83

; __device__ __forceinline__ void wconv_item(LAS float* scr, const WEnt& e, int item, int lane) {
;     ...
;     for (int i = 0; i < 32; ++i) vv[i] = sp[(size_t)(2 * i) * e.src_ld];
; #pragma unroll
;     for (int i = 0; i < 32; ++i) { float v = vv[i]; if (gp) v *= gp[2 * i]; scr[(2 * i + (lane >> 5)) * 33 + (lane & 31)] = (col >= 0) ? v : 0.f; }
.LBB0_1203:
	s_or_b64 exec, exec, s[8:9]
	s_waitcnt vmcnt(14)
	v_cndmask_b32_e32 v13, 0, v45, vcc
	v_add_u32_e32 v0, 0x1000, v32
	ds_write2_b32 v0, v12, v13 offset0:32 offset1:98
	s_and_saveexec_b64 s[8:9], s[38:39]
	s_xor_b64 s[8:9], exec, s[8:9]
	s_cbranch_execz .LBB0_1205
	s_waitcnt vmcnt(13)
	v_mul_f32_e32 v12, v44, v84
	v_cndmask_b32_e32 v12, 0, v12, vcc
	s_waitcnt vmcnt(12)
	v_mul_f32_e32 v43, v43, v85

; __device__ __forceinline__ void wconv_item(LAS float* scr, const WEnt& e, int item, int lane) {
;     ...
;     for (int i = 0; i < 32; ++i) vv[i] = sp[(size_t)(2 * i) * e.src_ld];
; #pragma unroll
;     for (int i = 0; i < 32; ++i) { float v = vv[i]; if (gp) v *= gp[2 * i]; scr[(2 * i + (lane >> 5)) * 33 + (lane & 31)] = (col >= 0) ? v : 0.f; }
.LBB0_1207:
	s_or_b64 exec, exec, s[8:9]
	s_waitcnt vmcnt(12)
	v_cndmask_b32_e32 v13, 0, v43, vcc
	ds_write2_b32 v0, v12, v13 offset0:164 offset1:230
	s_and_saveexec_b64 s[8:9], s[38:39]
	s_xor_b64 s[8:9], exec, s[8:9]
	s_cbranch_execz .LBB0_1209
	s_waitcnt vmcnt(11)
	v_mul_f32_e32 v0, v42, v86
	v_cndmask_b32_e32 v12, 0, v0, vcc
	s_waitcnt vmcnt(10)
	v_mul_f32_e32 v41, v41, v87

; __device__ __forceinline__ void wconv_item(LAS float* scr, const WEnt& e, int item, int lane) {
;     ...
;     for (int i = 0; i < 32; ++i) vv[i] = sp[(size_t)(2 * i) * e.src_ld];
; #pragma unroll
;     for (int i = 0; i < 32; ++i) { float v = vv[i]; if (gp) v *= gp[2 * i]; scr[(2 * i + (lane >> 5)) * 33 + (lane & 31)] = (col >= 0) ? v : 0.f; }
.LBB0_1211:
	s_or_b64 exec, exec, s[8:9]
	s_waitcnt vmcnt(10)
	v_cndmask_b32_e32 v13, 0, v41, vcc
	v_add_u32_e32 v0, 0x1400, v32
	ds_write2_b32 v0, v12, v13 offset0:40 offset1:106
	s_and_saveexec_b64 s[8:9], s[38:39]
	s_xor_b64 s[8:9], exec, s[8:9]
	s_cbranch_execz .LBB0_1213
	s_waitcnt vmcnt(9)
	v_mul_f32_e32 v12, v40, v88
	v_cndmask_b32_e32 v12, 0, v12, vcc
	s_waitcnt vmcnt(8)
	v_mul_f32_e32 v39, v39, v89

; __device__ __forceinline__ void wconv_item(LAS float* scr, const WEnt& e, int item, int lane) {
;     ...
;     for (int i = 0; i < 32; ++i) vv[i] = sp[(size_t)(2 * i) * e.src_ld];
; #pragma unroll
;     for (int i = 0; i < 32; ++i) { float v = vv[i]; if (gp) v *= gp[2 * i]; scr[(2 * i + (lane >> 5)) * 33 + (lane & 31)] = (col >= 0) ? v : 0.f; }
.LBB0_1215:
	s_or_b64 exec, exec, s[8:9]
	s_waitcnt vmcnt(8)
	v_cndmask_b32_e32 v13, 0, v39, vcc
	ds_write2_b32 v0, v12, v13 offset0:172 offset1:238
	s_and_saveexec_b64 s[8:9], s[38:39]
	s_xor_b64 s[8:9], exec, s[8:9]
	s_cbranch_execz .LBB0_1217
	s_waitcnt vmcnt(7)
	v_mul_f32_e32 v0, v38, v90
	v_cndmask_b32_e32 v12, 0, v0, vcc
	s_waitcnt vmcnt(6)
	v_mul_f32_e32 v37, v37, v91

; __device__ __forceinline__ void wconv_item(LAS float* scr, const WEnt& e, int item, int lane) {
;     ...
;     for (int i = 0; i < 32; ++i) vv[i] = sp[(size_t)(2 * i) * e.src_ld];
; #pragma unroll
;     for (int i = 0; i < 32; ++i) { float v = vv[i]; if (gp) v *= gp[2 * i]; scr[(2 * i + (lane >> 5)) * 33 + (lane & 31)] = (col >= 0) ? v : 0.f; }
.LBB0_1219:
	s_or_b64 exec, exec, s[8:9]
	s_waitcnt vmcnt(6)
	v_cndmask_b32_e32 v13, 0, v37, vcc
	v_add_u32_e32 v0, 0x1800, v32
	ds_write2_b32 v0, v12, v13 offset0:48 offset1:114
	s_and_saveexec_b64 s[8:9], s[38:39]
	s_xor_b64 s[8:9], exec, s[8:9]
	s_cbranch_execz .LBB0_1221
	s_waitcnt vmcnt(5)
	v_mul_f32_e32 v12, v36, v92
	v_cndmask_b32_e32 v12, 0, v12, vcc
	s_waitcnt vmcnt(4)
	v_mul_f32_e32 v35, v35, v93

; __device__ __forceinline__ void wconv_item(LAS float* scr, const WEnt& e, int item, int lane) {
;     ...
;     for (int i = 0; i < 32; ++i) vv[i] = sp[(size_t)(2 * i) * e.src_ld];
; #pragma unroll
;     for (int i = 0; i < 32; ++i) { float v = vv[i]; if (gp) v *= gp[2 * i]; scr[(2 * i + (lane >> 5)) * 33 + (lane & 31)] = (col >= 0) ? v : 0.f; }
.LBB0_1223:
	s_or_b64 exec, exec, s[8:9]
	s_waitcnt vmcnt(4)
	v_cndmask_b32_e32 v13, 0, v35, vcc
	ds_write2_b32 v0, v12, v13 offset0:180 offset1:246
	s_and_saveexec_b64 s[8:9], s[38:39]
	s_xor_b64 s[8:9], exec, s[8:9]
	s_cbranch_execz .LBB0_1225
	s_waitcnt vmcnt(3)
	v_mul_f32_e32 v0, v34, v94
	v_cndmask_b32_e32 v12, 0, v0, vcc
	s_waitcnt vmcnt(2)
	v_mul_f32_e32 v17, v17, v95

; __device__ __forceinline__ void wconv_item(LAS float* scr, const WEnt& e, int item, int lane) {
;     ...
;     for (int i = 0; i < 32; ++i) vv[i] = sp[(size_t)(2 * i) * e.src_ld];
; #pragma unroll
;     for (int i = 0; i < 32; ++i) { float v = vv[i]; if (gp) v *= gp[2 * i]; scr[(2 * i + (lane >> 5)) * 33 + (lane & 31)] = (col >= 0) ? v : 0.f; }
.LBB0_1227:
	s_or_b64 exec, exec, s[8:9]
	s_waitcnt vmcnt(2)
	v_cndmask_b32_e32 v13, 0, v17, vcc
	v_add_u32_e32 v0, 0x1c00, v32
	ds_write2_b32 v0, v12, v13 offset0:56 offset1:122
	s_and_saveexec_b64 s[8:9], s[38:39]
	s_xor_b64 s[8:9], exec, s[8:9]
	s_cbranch_execz .LBB0_1229
	s_waitcnt vmcnt(1)
	v_mul_f32_e32 v12, v16, v96
	v_cndmask_b32_e32 v12, 0, v12, vcc
	s_waitcnt vmcnt(0)
	v_mul_f32_e32 v7, v7, v97
